# adds attention QK MFMA order: each 32x32 score accumulator gets its four MFMAs back to back
# baseline (speedup 1.0000x reference)
.LBB0_90:
	s_lshl_b32 s21, s28, 1
	v_add_u32_e32 v213, s21, v225
	ds_read_b64_tr_b16 v[208:209], v213 offset:24576
	ds_read_b64_tr_b16 v[210:211], v213 offset:25088
	s_waitcnt lgkmcnt(9)
	v_mfma_f32_32x32x16_bf16 v[128:143], v[204:207], v[172:175], v[64:79]
	v_add_f32_e32 v112, v96, v97
	v_add_f32_e32 v112, v98, v112
	v_add_f32_e32 v112, v99, v112
	v_add_f32_e32 v112, v100, v112
	v_add_f32_e32 v112, v101, v112
	v_cvt_pk_bf16_f32 v164, v96, v97
	v_cvt_pk_bf16_f32 v165, v98, v99
	ds_read_b64_tr_b16 v[204:205], v213 offset:28672
	ds_read_b64_tr_b16 v[206:207], v213 offset:29184
	v_add_f32_e32 v96, v102, v112
	s_waitcnt lgkmcnt(10)
	v_mfma_f32_32x32x16_bf16 v[128:143], v[196:199], v[168:171], v[128:143]
	v_add_f32_e32 v96, v103, v96
	v_add_f32_e32 v96, v104, v96
	v_add_f32_e32 v144, v105, v96
	v_cvt_pk_bf16_f32 v166, v100, v101
	v_cvt_pk_bf16_f32 v167, v102, v103
	ds_read_b64_tr_b16 v[96:97], v213 offset:25600
	ds_read_b64_tr_b16 v[98:99], v213 offset:26112
	s_waitcnt lgkmcnt(11)
	v_mfma_f32_32x32x16_bf16 v[128:143], v[188:191], v[160:163], v[128:143]
	v_add_f32_e32 v100, v106, v144
	v_add_f32_e32 v100, v107, v100
	v_add_f32_e32 v100, v108, v100
	v_add_f32_e32 v144, v109, v100
	v_cvt_pk_bf16_f32 v156, v104, v105
	v_cvt_pk_bf16_f32 v157, v106, v107
	ds_read_b64_tr_b16 v[100:101], v213 offset:29696
	ds_read_b64_tr_b16 v[102:103], v213 offset:30208
	s_waitcnt lgkmcnt(12)
	v_mfma_f32_32x32x16_bf16 v[128:143], v[180:183], v[152:155], v[128:143]
	v_add_f32_e32 v104, v110, v144
	v_add_f32_e32 v104, v111, v104
	v_add_f32_e32 v104, v80, v104
	v_add_f32_e32 v144, v81, v104
	v_cvt_pk_bf16_f32 v158, v108, v109
	v_cvt_pk_bf16_f32 v159, v110, v111
	ds_read_b64_tr_b16 v[104:105], v213 offset:26624
	ds_read_b64_tr_b16 v[106:107], v213 offset:27136
	s_waitcnt lgkmcnt(13)
	v_mfma_f32_32x32x16_bf16 v[112:127], v[200:203], v[172:175], v[64:79]
	v_add_f32_e32 v108, v82, v144
	v_add_f32_e32 v108, v83, v108
	v_add_f32_e32 v108, v84, v108
	v_add_f32_e32 v144, v85, v108
	v_cvt_pk_bf16_f32 v148, v80, v81
	v_cvt_pk_bf16_f32 v149, v82, v83
	ds_read_b64_tr_b16 v[108:109], v213 offset:30720
	ds_read_b64_tr_b16 v[110:111], v213 offset:31232
	s_waitcnt lgkmcnt(14)
	v_mfma_f32_32x32x16_bf16 v[112:127], v[192:195], v[168:171], v[112:127]
	v_add_f32_e32 v80, v86, v144
	v_add_f32_e32 v80, v87, v80
	v_add_f32_e32 v80, v88, v80
	v_add_f32_e32 v80, v89, v80
	v_cvt_pk_bf16_f32 v150, v84, v85
	v_cvt_pk_bf16_f32 v151, v86, v87
	ds_read_b64_tr_b16 v[84:85], v213 offset:27648
	ds_read_b64_tr_b16 v[86:87], v213 offset:28160
	s_waitcnt lgkmcnt(14)
	v_mfma_f32_32x32x16_bf16 v[112:127], v[184:187], v[160:163], v[112:127]
	v_add_f32_e32 v80, v90, v80
	v_add_f32_e32 v80, v91, v80
	v_add_f32_e32 v80, v92, v80
	v_add_f32_e32 v80, v93, v80
	v_cvt_pk_bf16_f32 v144, v88, v89
	v_cvt_pk_bf16_f32 v145, v90, v91
	ds_read_b64_tr_b16 v[88:89], v213 offset:31744
	ds_read_b64_tr_b16 v[90:91], v213 offset:32256
	v_mfma_f32_32x32x16_bf16 v[112:127], v[176:179], v[152:155], v[112:127]
	v_add_f32_e32 v80, v94, v80
	v_add_f32_e32 v80, v95, v80
	v_add_f32_e32 v82, 0, v80
	v_cvt_pk_bf16_f32 v146, v92, v93
	v_cvt_pk_bf16_f32 v147, v94, v95
	v_lshl_add_u64 v[218:219], v[230:231], 0, s[36:37]
	v_lshl_add_u64 v[80:81], v[218:219], 0, s[92:93]
	s_add_i32 s21, s27, s18
	v_lshl_add_u64 v[216:217], v[214:215], 0, s[36:37]
	s_mov_b32 s24, m0
	s_mov_b32 m0, s21
	s_nop 0
	global_load_lds_dwordx4 v[80:81], off
	s_mov_b32 m0, s24
	v_lshl_add_u64 v[80:81], v[216:217], 0, s[0:1]
	s_lshl_b32 s21, s25, 1
	s_add_i32 s21, s21, s19
	s_mov_b32 s24, m0
	s_mov_b32 m0, s21
	s_nop 0
	global_load_lds_dwordx4 v[80:81], off
	s_mov_b32 m0, s24
	v_lshl_add_u64 v[80:81], v[216:217], 0, s[68:69]
	s_addk_i32 s21, 0x2000
	s_mov_b32 s24, m0
	s_mov_b32 m0, s21
	s_nop 0
	global_load_lds_dwordx4 v[80:81], off
	s_mov_b32 m0, s24
	v_max_f32_e32 v80, v129, v129
	v_max_f32_e32 v81, v128, v128
	v_max_f32_e32 v80, v81, v80
	v_max3_f32 v81, v130, v131, v113
	v_max3_f32 v80, v80, v112, v114
	v_max3_f32 v80, v80, v115, v132
	v_max3_f32 v81, v81, v134, v135
	v_max3_f32 v80, v80, v133, v116
	v_max3_f32 v81, v81, v118, v119
	v_max3_f32 v80, v80, v117, v136
	v_max3_f32 v81, v81, v138, v139
	v_max3_f32 v80, v80, v137, v120
	v_max3_f32 v81, v81, v122, v123
	v_max3_f32 v80, v80, v121, v140
	v_max3_f32 v81, v81, v142, v143
	v_max3_f32 v80, v80, v141, v124
	v_max3_f32 v81, v81, v126, v127
	v_max3_f32 v80, v80, v125, v81
	v_mov_b32_e32 v81, v80
	s_nop 1
	v_permlane32_swap_b32_e32 v80, v81
	v_max_f32_e32 v81, v81, v81
	v_max_f32_e32 v80, v80, v80
	v_max_f32_e32 v80, v80, v81
	v_cmp_lt_f32_e32 vcc, s74, v80
	s_cmp_lg_u64 vcc, 0
	v_add_f32_e32 v227, v227, v82
	s_cselect_b64 s[38:39], -1, 0
	s_cbranch_vccnz .LBB0_98

.LBB0_93:
	s_add_i32 s21, s25, 0x2000
	s_cmpk_lg_i32 s25, 0x4000
	s_cselect_b32 s21, s21, 0
	s_lshl_b32 s24, s27, 1
	v_add_u32_e32 v228, s24, v225
	ds_read_b64_tr_b16 v[204:205], v228 offset:24576
	ds_read_b64_tr_b16 v[206:207], v228 offset:25088
	v_mfma_f32_32x32x16_bf16 v[96:111], v[80:83], v[172:175], v[64:79]
	v_add_f32_e32 v84, v128, v129
	v_add_f32_e32 v84, v130, v84
	v_add_f32_e32 v84, v131, v84
	v_add_f32_e32 v84, v132, v84
	v_add_f32_e32 v84, v133, v84
	v_cvt_pk_bf16_f32 v164, v128, v129
	v_cvt_pk_bf16_f32 v165, v130, v131
	ds_read_b64_tr_b16 v[208:209], v228 offset:28672
	ds_read_b64_tr_b16 v[210:211], v228 offset:29184
	v_add_f32_e32 v80, v134, v84
	v_add_f32_e32 v80, v135, v80
	v_add_f32_e32 v80, v136, v80
	v_add_f32_e32 v144, v137, v80
	v_mfma_f32_32x32x16_bf16 v[96:111], v[200:203], v[168:171], v[96:111]
	v_cvt_pk_bf16_f32 v166, v132, v133
	v_cvt_pk_bf16_f32 v167, v134, v135
	ds_read_b64_tr_b16 v[128:129], v228 offset:25600
	ds_read_b64_tr_b16 v[130:131], v228 offset:26112
	v_mfma_f32_32x32x16_bf16 v[96:111], v[188:191], v[160:163], v[96:111]
	v_add_f32_e32 v132, v138, v144
	v_add_f32_e32 v132, v139, v132
	v_add_f32_e32 v132, v140, v132
	v_add_f32_e32 v144, v141, v132
	v_cvt_pk_bf16_f32 v156, v136, v137
	v_cvt_pk_bf16_f32 v157, v138, v139
	ds_read_b64_tr_b16 v[132:133], v228 offset:29696
	ds_read_b64_tr_b16 v[134:135], v228 offset:30208
	v_mfma_f32_32x32x16_bf16 v[96:111], v[180:183], v[152:155], v[96:111]
	v_add_f32_e32 v136, v142, v144
	v_add_f32_e32 v136, v143, v136
	v_add_f32_e32 v136, v112, v136
	v_add_f32_e32 v144, v113, v136
	v_cvt_pk_bf16_f32 v158, v140, v141
	v_cvt_pk_bf16_f32 v159, v142, v143
	ds_read_b64_tr_b16 v[136:137], v228 offset:26624
	ds_read_b64_tr_b16 v[138:139], v228 offset:27136
	v_mfma_f32_32x32x16_bf16 v[80:95], v[196:199], v[172:175], v[64:79]
	v_add_f32_e32 v140, v114, v144
	v_add_f32_e32 v140, v115, v140
	v_add_f32_e32 v140, v116, v140
	v_add_f32_e32 v140, v117, v140
	v_cvt_pk_bf16_f32 v148, v112, v113
	v_cvt_pk_bf16_f32 v149, v114, v115
	ds_read_b64_tr_b16 v[112:113], v228 offset:30720
	ds_read_b64_tr_b16 v[114:115], v228 offset:31232
	v_mfma_f32_32x32x16_bf16 v[80:95], v[192:195], v[168:171], v[80:95]
	v_add_f32_e32 v140, v118, v140
	v_add_f32_e32 v140, v119, v140
	v_add_f32_e32 v140, v120, v140
	v_add_f32_e32 v140, v121, v140
	v_cvt_pk_bf16_f32 v150, v116, v117
	v_cvt_pk_bf16_f32 v151, v118, v119
	ds_read_b64_tr_b16 v[116:117], v228 offset:27648
	ds_read_b64_tr_b16 v[118:119], v228 offset:28160
	v_mfma_f32_32x32x16_bf16 v[80:95], v[184:187], v[160:163], v[80:95]
	v_add_f32_e32 v140, v122, v140
	v_add_f32_e32 v140, v123, v140
	v_add_f32_e32 v140, v124, v140
	v_add_f32_e32 v140, v125, v140
	v_cvt_pk_bf16_f32 v144, v120, v121
	v_cvt_pk_bf16_f32 v145, v122, v123
	ds_read_b64_tr_b16 v[120:121], v228 offset:31744
	ds_read_b64_tr_b16 v[122:123], v228 offset:32256
	v_mfma_f32_32x32x16_bf16 v[80:95], v[176:179], v[152:155], v[80:95]
	v_add_f32_e32 v140, v126, v140
	v_add_f32_e32 v140, v127, v140
	v_add_f32_e32 v140, 0, v140
	v_cvt_pk_bf16_f32 v146, v124, v125
	v_cvt_pk_bf16_f32 v147, v126, v127
	s_mov_b64 s[28:29], 0x460000
	v_lshl_add_u64 v[124:125], v[218:219], 0, s[28:29]
	s_add_i32 s24, s25, s18
	s_mov_b64 s[28:29], 0x12aa1000
	s_mov_b32 s27, m0
	s_mov_b32 m0, s24
	s_nop 0
	global_load_lds_dwordx4 v[124:125], off
	s_mov_b32 m0, s27
	v_lshl_add_u64 v[124:125], v[216:217], 0, s[28:29]
	s_lshl_b32 s24, s21, 1
	s_mov_b64 s[28:29], 0x12aa1080
	s_add_i32 s24, s24, s19
	s_mov_b32 s27, m0
	s_mov_b32 m0, s24
	s_nop 0
	global_load_lds_dwordx4 v[124:125], off
	s_mov_b32 m0, s27
	v_lshl_add_u64 v[124:125], v[216:217], 0, s[28:29]
	s_addk_i32 s24, 0x2000
	s_mov_b32 s27, m0
	s_mov_b32 m0, s24
	s_nop 0
	global_load_lds_dwordx4 v[124:125], off
	s_mov_b32 m0, s27
	v_max_f32_e32 v124, v97, v97
	v_max_f32_e32 v125, v96, v96
	v_max_f32_e32 v124, v125, v124
	v_max3_f32 v125, v98, v99, v81
	v_max3_f32 v124, v124, v80, v82
	v_max3_f32 v124, v124, v83, v100
	v_max3_f32 v125, v125, v102, v103
	v_max3_f32 v124, v124, v101, v84
	v_max3_f32 v125, v125, v86, v87
	v_max3_f32 v124, v124, v85, v104
	v_max3_f32 v125, v125, v106, v107
	v_max3_f32 v124, v124, v105, v88
	v_max3_f32 v125, v125, v90, v91
	v_max3_f32 v124, v124, v89, v108
	v_max3_f32 v125, v125, v110, v111
	v_max3_f32 v124, v124, v109, v92
	v_max3_f32 v125, v125, v94, v95
	v_max3_f32 v124, v124, v93, v125
	v_mov_b32_e32 v125, v124
	s_nop 1
	v_permlane32_swap_b32_e32 v124, v125
	v_max_f32_e32 v125, v125, v125
	v_max_f32_e32 v124, v124, v124
	v_max_f32_e32 v124, v124, v125
	v_cmp_lt_f32_e32 vcc, s74, v124
	s_cmp_lg_u64 vcc, 0
	v_add_f32_e32 v227, v227, v140
	s_cselect_b64 s[38:39], -1, 0
	s_cbranch_vccnz .LBB0_101
